# c15 + one static s_setprio 1 for waves 4-7 (the second wave of each SIMD) during the attention phase
# speedup vs baseline: 1.0106x; 1.0106x over previous
; #define LAS __attribute__((address_space(3)))
; DI int otid() { int t = raw_tid(); asm volatile("" : "+v"(t)); return t; }
; DI int vblock() { const int G = gridDim.x, bx = blockIdx.x; return (G & 7) == 0 ? (bx & 7) * (G >> 3) + (bx >> 3) : bx; }
; DI void attn_phase(LAS unsigned char* L, const bf16_t* P, bf16_t* Oo, const float* rpb, int nseq) {
;     LAS float* rpbL = (LAS float*)(L + ATT_RPB_OFF);
;     const int tid = otid();
;     for (int i = tid; i < 8 * 465; i += NTHR) rpbL[i] = rpb[i] * LOG2E;
;     __syncthreads();
;     const int wave = tid >> 6, lane = tid & 63;
;     LAS unsigned char* LV = L + ATT_V_OFF + wave * ATT_W_BYTES;
;     const int nitems = nseq * 1024, nw = gridDim.x * 8;
;     for (int it = vblock() * 8 + wave; it < 2 * nitems; it += nw) {
.LBB0_293:
	s_or_b64 exec, exec, s[0:1]
	v_readfirstlane_b32 s6, v195
	s_andn2_b32 s6, s6, 63
	s_mov_b64 s[4:5], s[94:95]
	s_mov_b64 s[0:1], s[94:95]
	s_waitcnt lgkmcnt(0)
	v_add_u32_e32 v2, s6, v205
	s_movk_i32 s6, 0xe88
	s_barrier
	v_readfirstlane_b32 s100, v195
	s_nop 0
	s_bitcmp1_b32 s100, 8
	s_cbranch_scc0 .Lattn_prio_skip
	s_setprio 1
.Lattn_prio_skip:
	s_nop 0
	v_cmp_gt_i32_e32 vcc, s6, v2
	s_and_saveexec_b64 s[6:7], vcc
	s_cbranch_execz .LBB0_306
	v_max_i32_e32 v0, 0xc88, v2
	v_sub_u32_e32 v0, v0, v2
	v_add_u32_e32 v0, 0x1ff, v0
	s_movk_i32 s8, 0x1ff
	v_cmp_lt_u32_e32 vcc, s8, v0
	s_mov_b64 s[10:11], -1
	v_mov_b32_e32 v4, v2
	s_and_saveexec_b64 s[8:9], vcc
	s_cbranch_execz .LBB0_303
	v_lshrrev_b32_e32 v0, 9, v0
	v_add_u32_e32 v4, -1, v0
	v_add_u32_e32 v3, 0x200, v2
	v_lshrrev_b32_e32 v5, 1, v4
	v_add_u32_e32 v6, 1, v5
	v_cmp_lt_u32_e32 vcc, 13, v4
	v_mov_b32_e32 v9, 0
	v_mov_b64_e32 v[4:5], v[2:3]
	s_and_saveexec_b64 s[10:11], vcc
	s_cbranch_execz .LBB0_299
	v_lshlrev_b32_e32 v4, 2, v2
	v_and_b32_e32 v7, -8, v6
	v_add3_u32 v8, 0, 64, v4
	s_mov_b32 s14, 0
	s_mov_b64 s[12:13], 0
	v_mov_b64_e32 v[4:5], v[2:3]

; DI int raw_tid() { return __builtin_amdgcn_readfirstlane((int)threadIdx.x >> 6) * 64 + (int)__builtin_amdgcn_mbcnt_hi(~0u, __builtin_amdgcn_mbcnt_lo(~0u, 0u)); }
; DI void attn_phase(LAS unsigned char* L, const bf16_t* P, bf16_t* Oo, const float* rpb, int nseq) {
;     ...
;     __syncthreads();
; DI void xcd_barrier(const XcdBarrier& b) {
;     asm volatile("s_waitcnt vmcnt(0)" ::: "memory");
;     __syncthreads();
;     if (raw_tid() == 0) {
;         unsigned* bar = b.bar;
;         __builtin_amdgcn_s_waitcnt(0);
;         unsigned nloc = b.st[0], nx = b.st[1];
;         if (nloc == 0u) { xcd_barrier_complete(bar, b.x, nloc, nx); b.st[0] = nloc; b.st[1] = nx; }
.LBB0_355:
	s_or_b64 exec, exec, s[60:61]
	s_setprio 0
	v_readfirstlane_b32 s0, v195
	s_barrier
	s_waitcnt vmcnt(0)
	s_andn2_b32 s0, s0, 63
	s_sub_i32 s0, 0, s0
	v_cmp_eq_u32_e32 vcc, s0, v205
	s_barrier
	s_and_saveexec_b64 s[0:1], vcc
	v_readlane_b32 s92, v255, 33
	v_readlane_b32 s93, v255, 34
	v_readlane_b32 s94, v255, 35
	v_readlane_b32 s95, v255, 36
	v_readlane_b32 s20, v255, 27
	v_readlane_b32 s87, v255, 38
	v_readlane_b32 s85, v255, 40
	v_readlane_b32 s86, v255, 41
	v_readlane_b32 s21, v255, 28
	s_cbranch_execz .LBB0_406
	v_readlane_b32 s4, v255, 23
	s_waitcnt vmcnt(0) expcnt(0) lgkmcnt(0)
	s_nop 0
	v_mov_b32_e32 v0, s4
	ds_read_b32 v3, v0
	v_readlane_b32 s4, v255, 24
	s_waitcnt lgkmcnt(0)
	v_cmp_ne_u32_e32 vcc, 0, v3
	v_mov_b32_e32 v0, s4
	ds_read_b32 v2, v0
	s_cbranch_vccnz .LBB0_370
	s_mov_b32 s9, 0
	s_branch .LBB0_359
